# compressed-branch loop: overlap-weight operands of the importance MFMAs built per packed dword (one compare + select) instead of per element
# speedup vs baseline: 1.0156x; 1.0088x over previous
; #define LAS __attribute__((address_space(3)))
; #define LDS_WAIT() asm volatile("s_waitcnt lgkmcnt(0)" ::: "memory")
; #define MFMA32(a, b, c) __builtin_amdgcn_mfma_f32_32x32x16_bf16((a), (b), (c), 0, 0, 0)
; DI s16x4 vtr(const LAS unsigned char* p) { return __builtin_bit_cast(s16x4, __builtin_amdgcn_ds_read_tr16_b64_v4i16((LAS v4i16_t*)p)); }
; DI bf16x8 cat8(s16x4 lo, s16x4 hi) { return __builtin_shufflevector(lo, hi, 0, 1, 2, 3, 4, 5, 6, 7); }
; template <bool CMP> DI void tile_compute(LAS unsigned char* lds, int buf, const bf16x8 (&q)[4], int lo, int hv, ASt& st, f32x16& imp0, f32x16& imp1, int jt, LAS float* wsf, int lane) {
;     ...
;     const float msub = (!anyPart && dead) ? 1e30f : mnew;
; #pragma unroll
;     for (int rg = 0; rg < 16; ++rg) { p0[rg] = __builtin_amdgcn_exp2f(p0[rg] - msub); p1[rg] = __builtin_amdgcn_exp2f(p1[rg] - msub); sum += p0[rg] + p1[rg]; }
;     st.l = st.l * alpha + sum;
;     if (__builtin_amdgcn_ballot_w64(alpha != 1.f) != 0ull) {
;         if (hi == 0) wsf[r] = alpha;
;         LDS_WAIT();
; #pragma unroll
;         for (int g4 = 0; g4 < 4; ++g4) { const f32x4 f = *(const LAS f32x4*)(wsf + 8 * g4 + 4 * hi);
; #pragma unroll
;             for (int k = 0; k < 4; ++k) { st.o0[4 * g4 + k] *= f[k]; st.o1[4 * g4 + k] *= f[k]; if (CMP) { imp0[4 * g4 + k] *= f[k]; imp1[4 * g4 + k] *= f[k]; } } }
;         LDS_WAIT();
;     }
;     bf16x8 pa[4];
;     pa[0] = pack8(p0[0], p0[1], p0[2], p0[3], p0[4], p0[5], p0[6], p0[7]); pa[1] = pack8(p0[8], p0[9], p0[10], p0[11], p0[12], p0[13], p0[14], p0[15]);
;     pa[2] = pack8(p1[0], p1[1], p1[2], p1[3], p1[4], p1[5], p1[6], p1[7]); pa[3] = pack8(p1[8], p1[9], p1[10], p1[11], p1[12], p1[13], p1[14], p1[15]);
;     const LAS unsigned char* vb = lds + A_VT + buf * 8192 + (4 * hi + ((lane & 15) >> 2)) * 64 + ((lane >> 4) & 1) * 32 + (lane & 3) * 8;
; #pragma unroll
;     for (int s = 0; s < 4; ++s) {
;         const bf16x8 v0 = cat8(vtr(vb + s * 1024), vtr(vb + s * 1024 + 512));
;         const bf16x8 v1 = cat8(vtr(vb + 4096 + s * 1024), vtr(vb + 4096 + s * 1024 + 512));
;         st.o0 = MFMA32(pa[s], v0, st.o0); st.o1 = MFMA32(pa[s], v1, st.o1);
;     }
.LBB0_555:
	v_cndmask_b32_e64 v234, v141, v223, s[78:79]
	v_sub_f32_e32 v84, v84, v234
	v_sub_f32_e32 v68, v68, v234
	v_exp_f32_e32 v235, v84
	v_exp_f32_e32 v68, v68
	v_sub_f32_e32 v85, v85, v234
	v_sub_f32_e32 v69, v69, v234
	v_exp_f32_e32 v85, v85
	v_exp_f32_e32 v69, v69
	v_sub_f32_e32 v86, v86, v234
	v_sub_f32_e32 v70, v70, v234
	v_exp_f32_e32 v86, v86
	v_exp_f32_e32 v70, v70
	v_sub_f32_e32 v87, v87, v234
	v_sub_f32_e32 v71, v71, v234
	v_exp_f32_e32 v87, v87
	v_exp_f32_e32 v71, v71
	v_add_f32_e32 v84, v68, v235
	v_add_f32_e32 v84, 0, v84
	v_add_f32_e32 v236, v69, v85
	v_add_f32_e32 v84, v236, v84
	v_add_f32_e32 v236, v70, v86
	v_add_f32_e32 v84, v236, v84
	v_add_f32_e32 v236, v71, v87
	v_sub_f32_e32 v88, v88, v234
	v_sub_f32_e32 v72, v72, v234
	v_add_f32_e32 v84, v236, v84
	v_exp_f32_e32 v88, v88
	v_exp_f32_e32 v236, v72
	v_sub_f32_e32 v73, v73, v234
	v_exp_f32_e32 v237, v73
	v_sub_f32_e32 v74, v74, v234
	v_add_f32_e32 v72, v236, v88
	v_add_f32_e32 v72, v72, v84
	v_sub_f32_e32 v84, v89, v234
	v_exp_f32_e32 v89, v84
	v_sub_f32_e32 v75, v75, v234
	v_exp_f32_e32 v75, v75
	v_sub_f32_e32 v76, v76, v234
	v_add_f32_e32 v73, v237, v89
	v_add_f32_e32 v72, v73, v72
	v_sub_f32_e32 v73, v90, v234
	v_exp_f32_e32 v73, v73
	v_exp_f32_e32 v90, v74
	v_sub_f32_e32 v77, v77, v234
	v_sub_f32_e32 v78, v78, v234
	v_sub_f32_e32 v79, v79, v234
	v_add_f32_e32 v74, v90, v73
	v_add_f32_e32 v72, v74, v72
	v_sub_f32_e32 v74, v91, v234
	v_exp_f32_e32 v74, v74
	v_sub_f32_e32 v80, v80, v234
	v_subrev_u32_e32 v231, 64, v231
	v_add_f32_e32 v84, v75, v74
	v_add_f32_e32 v72, v84, v72
	v_sub_f32_e32 v84, v92, v234
	v_exp_f32_e32 v91, v84
	v_exp_f32_e32 v92, v76
	v_cvt_pk_bf16_f32 v75, v90, v75
	v_add_f32_e32 v76, v92, v91
	v_add_f32_e32 v72, v76, v72
	v_sub_f32_e32 v76, v93, v234
	v_exp_f32_e32 v76, v76
	v_exp_f32_e32 v93, v77
	s_nop 0
	v_add_f32_e32 v77, v93, v76
	v_add_f32_e32 v72, v77, v72
	v_sub_f32_e32 v77, v94, v234
	v_exp_f32_e32 v77, v77
	v_exp_f32_e32 v94, v78
	v_cvt_pk_bf16_f32 v76, v91, v76
	v_add_f32_e32 v78, v94, v77
	v_add_f32_e32 v72, v78, v72
	v_sub_f32_e32 v78, v95, v234
	v_exp_f32_e32 v78, v78
	v_exp_f32_e32 v95, v79
	v_cvt_pk_bf16_f32 v77, v77, v78
	v_add_f32_e32 v79, v95, v78
	v_add_f32_e32 v72, v79, v72
	v_sub_f32_e32 v79, v96, v234
	v_exp_f32_e32 v79, v79
	v_exp_f32_e32 v96, v80
	s_nop 0
	v_add_f32_e32 v80, v96, v79
	v_add_f32_e32 v72, v80, v72
	v_sub_f32_e32 v80, v97, v234
	v_exp_f32_e32 v97, v80
	v_sub_f32_e32 v80, v81, v234
	v_exp_f32_e32 v238, v80
	v_cvt_pk_bf16_f32 v81, v86, v87
	v_cvt_pk_bf16_f32 v78, v79, v97
	v_add_f32_e32 v80, v238, v97
	v_add_f32_e32 v72, v80, v72
	v_sub_f32_e32 v80, v98, v234
	v_exp_f32_e32 v98, v80
	v_sub_f32_e32 v80, v82, v234
	v_exp_f32_e32 v239, v80
	v_cvt_pk_bf16_f32 v82, v88, v89
	v_add_f32_e32 v80, v239, v98
	v_add_f32_e32 v72, v80, v72
	v_sub_f32_e32 v80, v99, v234
	v_exp_f32_e32 v99, v80
	v_sub_f32_e32 v80, v83, v234
	v_exp_f32_e32 v234, v80
	v_cvt_pk_bf16_f32 v83, v73, v74
	v_cvt_pk_bf16_f32 v79, v98, v99
	v_cvt_pk_bf16_f32 v73, v70, v71
	v_add_f32_e32 v80, v234, v99
	v_add_f32_e32 v84, v80, v72
	v_cvt_pk_bf16_f32 v80, v235, v85
	v_add_u32_e32 v85, s90, v196
	v_add3_u32 v85, v85, v197, v198
	v_cvt_pk_bf16_f32 v72, v68, v69
	v_cvt_pk_bf16_f32 v68, v92, v93
	ds_read_b64_tr_b16 v[86:87], v85 offset:16384
	ds_read_b64_tr_b16 v[88:89], v85 offset:16896
	ds_read_b64_tr_b16 v[90:91], v85 offset:20480
	ds_read_b64_tr_b16 v[92:93], v85 offset:20992
	s_waitcnt lgkmcnt(0)
	v_mfma_f32_32x32x16_bf16 v[52:67], v[80:83], v[86:89], v[52:67]
	v_cvt_pk_bf16_f32 v74, v236, v237
	v_cvt_pk_bf16_f32 v69, v94, v95
	v_cvt_pk_bf16_f32 v70, v96, v238
	v_cvt_pk_bf16_f32 v71, v239, v234
	v_fmac_f32_e32 v84, v232, v233
	v_mfma_f32_32x32x16_bf16 v[36:51], v[80:83], v[90:93], v[36:51]
	ds_read_b64_tr_b16 v[86:87], v85 offset:17408
	ds_read_b64_tr_b16 v[88:89], v85 offset:17920
	ds_read_b64_tr_b16 v[90:91], v85 offset:21504
	ds_read_b64_tr_b16 v[92:93], v85 offset:22016
	s_waitcnt lgkmcnt(0)
	v_mfma_f32_32x32x16_bf16 v[52:67], v[76:79], v[86:89], v[52:67]
	v_mfma_f32_32x32x16_bf16 v[36:51], v[76:79], v[90:93], v[36:51]
	ds_read_b64_tr_b16 v[86:87], v85 offset:18432
	ds_read_b64_tr_b16 v[88:89], v85 offset:18944
	ds_read_b64_tr_b16 v[90:91], v85 offset:22528
	ds_read_b64_tr_b16 v[92:93], v85 offset:23040
	s_waitcnt lgkmcnt(0)
; #define MFMA32(a, b, c) __builtin_amdgcn_mfma_f32_32x32x16_bf16((a), (b), (c), 0, 0, 0)
; DI s16x4 vtr(const LAS unsigned char* p) { return __builtin_bit_cast(s16x4, __builtin_amdgcn_ds_read_tr16_b64_v4i16((LAS v4i16_t*)p)); }
; DI bf16x8 cat8(s16x4 lo, s16x4 hi) { return __builtin_shufflevector(lo, hi, 0, 1, 2, 3, 4, 5, 6, 7); }
; template <bool CMP> DI void tile_compute(LAS unsigned char* lds, int buf, const bf16x8 (&q)[4], int lo, int hv, ASt& st, f32x16& imp0, f32x16& imp1, int jt, LAS float* wsf, int lane) {
;     ...
;     for (int s = 0; s < 4; ++s) {
;         const bf16x8 v0 = cat8(vtr(vb + s * 1024), vtr(vb + s * 1024 + 512));
;         const bf16x8 v1 = cat8(vtr(vb + 4096 + s * 1024), vtr(vb + 4096 + s * 1024 + 512));
;         st.o0 = MFMA32(pa[s], v0, st.o0); st.o1 = MFMA32(pa[s], v1, st.o1);
;     }
;     if (CMP) {
; #pragma unroll
;         for (int s = 0; s < 4; ++s) {
;             bf16x8 w0, w1;
; #pragma unroll
;             for (int j = 0; j < 8; ++j) { const int jj = 64 * jt + 16 * s + 8 * (j >> 2) + 4 * hi + (j & 3);
;                 const int n0 = r, n1 = 32 + r;
;                 w0[j] = (jj >= 4 * n0 - 1 && jj <= 4 * n0 + 3) ? (short)0x3F80 : (short)0;
;                 w1[j] = (jj >= 4 * n1 - 1 && jj <= 4 * n1 + 3) ? (short)0x3F80 : (short)0; }
;             imp0 = MFMA32(pa[s], w0, imp0); imp1 = MFMA32(pa[s], w1, imp1); asm volatile("" ::: "memory");
;         }
;     }
	v_mfma_f32_32x32x16_bf16 v[52:67], v[72:75], v[86:89], v[52:67]
	v_mfma_f32_32x32x16_bf16 v[36:51], v[72:75], v[90:93], v[36:51]
	ds_read_b64_tr_b16 v[86:87], v85 offset:19456
	ds_read_b64_tr_b16 v[88:89], v85 offset:19968
	ds_read_b64_tr_b16 v[90:91], v85 offset:23552
	ds_read_b64_tr_b16 v[92:93], v85 offset:24064
	v_add_u32_e32 v85, s14, v148
	v_sub_u32_e32 v98, v85, v193
	v_mov_b32_e32 v96, 0x3f803f80
	v_mov_b32_e32 v97, 0x3f800000
	s_waitcnt lgkmcnt(0)
	v_mfma_f32_32x32x16_bf16 v[52:67], v[68:71], v[86:89], v[52:67]
	v_mfma_f32_32x32x16_bf16 v[36:51], v[68:71], v[90:93], v[36:51]
	s_add_i32 s14, s14, 64
	v_add_u32_e32 v94, 0, v98
	v_cmp_eq_u32_e32 vcc, 0, v94
	v_cmp_eq_u32_e64 s[78:79], -4, v94
	v_cmp_eq_u32_e64 s[12:13], -8, v94
	v_cndmask_b32_e32 v86, 0, v96, vcc
	v_cmp_eq_u32_e32 vcc, -12, v94
	v_cndmask_b32_e64 v87, v86, v97, s[78:79]
	v_cndmask_b32_e64 v88, 0, v96, s[12:13]
	v_cndmask_b32_e32 v89, v88, v97, vcc
	s_nop 1
	v_mfma_f32_32x32x16_bf16 v[20:35], v[80:83], v[86:89], v[20:35]
	v_add_u32_e32 v95, 0xffffff80, v98
	v_cmp_eq_u32_e32 vcc, 0, v95
	v_cmp_eq_u32_e64 s[78:79], -4, v95
	v_cmp_eq_u32_e64 s[12:13], -8, v95
	v_cndmask_b32_e32 v86, 0, v96, vcc
	v_cmp_eq_u32_e32 vcc, -12, v95
	v_cndmask_b32_e64 v87, v86, v97, s[78:79]
	v_cndmask_b32_e64 v88, 0, v96, s[12:13]
	v_cndmask_b32_e32 v89, v88, v97, vcc
	s_nop 1
	v_mfma_f32_32x32x16_bf16 v[4:19], v[80:83], v[86:89], v[4:19]
	v_add_u32_e32 v94, 16, v98
	v_cmp_eq_u32_e32 vcc, 0, v94
	v_cmp_eq_u32_e64 s[78:79], -4, v94
	v_cmp_eq_u32_e64 s[12:13], -8, v94
	v_cndmask_b32_e32 v80, 0, v96, vcc
	v_cmp_eq_u32_e32 vcc, -12, v94
	v_cndmask_b32_e64 v81, v80, v97, s[78:79]
	v_cndmask_b32_e64 v82, 0, v96, s[12:13]
	v_cndmask_b32_e32 v83, v82, v97, vcc
	s_nop 1
	v_mfma_f32_32x32x16_bf16 v[20:35], v[76:79], v[80:83], v[20:35]
	v_add_u32_e32 v95, 0xffffff90, v98
	v_cmp_eq_u32_e32 vcc, 0, v95
	v_cmp_eq_u32_e64 s[78:79], -4, v95
	v_cmp_eq_u32_e64 s[12:13], -8, v95
	v_cndmask_b32_e32 v80, 0, v96, vcc
	v_cmp_eq_u32_e32 vcc, -12, v95
	v_cndmask_b32_e64 v81, v80, v97, s[78:79]
	v_cndmask_b32_e64 v82, 0, v96, s[12:13]
	v_cndmask_b32_e32 v83, v82, v97, vcc
	s_nop 1
	v_mfma_f32_32x32x16_bf16 v[4:19], v[76:79], v[80:83], v[4:19]
	v_add_u32_e32 v94, 32, v98
	v_cmp_eq_u32_e32 vcc, 0, v94
	v_cmp_eq_u32_e64 s[78:79], -4, v94
	v_cmp_eq_u32_e64 s[12:13], -8, v94
	v_cndmask_b32_e32 v76, 0, v96, vcc
	v_cmp_eq_u32_e32 vcc, -12, v94
	v_cndmask_b32_e64 v77, v76, v97, s[78:79]
	v_cndmask_b32_e64 v78, 0, v96, s[12:13]
	v_cndmask_b32_e32 v79, v78, v97, vcc
	s_nop 1
	v_mfma_f32_32x32x16_bf16 v[20:35], v[72:75], v[76:79], v[20:35]
	v_add_u32_e32 v95, 0xffffffa0, v98
	v_cmp_eq_u32_e32 vcc, 0, v95
	v_cmp_eq_u32_e64 s[78:79], -4, v95
	v_cmp_eq_u32_e64 s[12:13], -8, v95
	v_cndmask_b32_e32 v76, 0, v96, vcc
	v_cmp_eq_u32_e32 vcc, -12, v95
	v_cndmask_b32_e64 v77, v76, v97, s[78:79]
	v_cndmask_b32_e64 v78, 0, v96, s[12:13]
	v_cndmask_b32_e32 v79, v78, v97, vcc
	s_nop 1
	v_mfma_f32_32x32x16_bf16 v[4:19], v[72:75], v[76:79], v[4:19]
	s_add_u32 s88, s88, 0x2000
	s_addc_u32 s89, s89, 0
	v_add_u32_e32 v94, 48, v98
	v_cmp_eq_u32_e32 vcc, 0, v94
	v_cmp_eq_u32_e64 s[78:79], -4, v94
	v_cmp_eq_u32_e64 s[12:13], -8, v94
	v_cndmask_b32_e32 v72, 0, v96, vcc
	v_cmp_eq_u32_e32 vcc, -12, v94
	v_cndmask_b32_e64 v73, v72, v97, s[78:79]
	v_cndmask_b32_e64 v74, 0, v96, s[12:13]
	v_cndmask_b32_e32 v75, v74, v97, vcc
	s_nop 1
	v_mfma_f32_32x32x16_bf16 v[20:35], v[68:71], v[72:75], v[20:35]
	s_add_i32 s3, s3, 1
	s_cmp_eq_u32 s84, s14
	v_add_u32_e32 v95, 0xffffffb0, v98
	v_cmp_eq_u32_e32 vcc, 0, v95
	v_cmp_eq_u32_e64 s[78:79], -4, v95
	v_cmp_eq_u32_e64 s[12:13], -8, v95
	v_cndmask_b32_e32 v72, 0, v96, vcc
	v_cmp_eq_u32_e32 vcc, -12, v95
	v_cndmask_b32_e64 v73, v72, v97, s[78:79]
	v_cndmask_b32_e64 v74, 0, v96, s[12:13]
	v_cndmask_b32_e32 v75, v74, v97, vcc
	s_nop 1
	v_mfma_f32_32x32x16_bf16 v[4:19], v[68:71], v[72:75], v[4:19]
	s_cbranch_scc1 .LBB0_557
	v_mov_b32_e32 v232, v84
	v_mov_b32_e32 v233, v141
	s_branch .LBB0_547

; #define LAS __attribute__((address_space(3)))
; #define LDS_WAIT() asm volatile("s_waitcnt lgkmcnt(0)" ::: "memory")
; #define MFMA32(a, b, c) __builtin_amdgcn_mfma_f32_32x32x16_bf16((a), (b), (c), 0, 0, 0)
; DI s16x4 vtr(const LAS unsigned char* p) { return __builtin_bit_cast(s16x4, __builtin_amdgcn_ds_read_tr16_b64_v4i16((LAS v4i16_t*)p)); }
; DI bf16x8 cat8(s16x4 lo, s16x4 hi) { return __builtin_shufflevector(lo, hi, 0, 1, 2, 3, 4, 5, 6, 7); }
; template <bool CMP> DI void tile_compute(LAS unsigned char* lds, int buf, const bf16x8 (&q)[4], int lo, int hv, ASt& st, f32x16& imp0, f32x16& imp1, int jt, LAS float* wsf, int lane) {
;     ...
;     const float msub = (!anyPart && dead) ? 1e30f : mnew;
; #pragma unroll
;     for (int rg = 0; rg < 16; ++rg) { p0[rg] = __builtin_amdgcn_exp2f(p0[rg] - msub); p1[rg] = __builtin_amdgcn_exp2f(p1[rg] - msub); sum += p0[rg] + p1[rg]; }
;     st.l = st.l * alpha + sum;
;     if (__builtin_amdgcn_ballot_w64(alpha != 1.f) != 0ull) {
;         if (hi == 0) wsf[r] = alpha;
;         LDS_WAIT();
; #pragma unroll
;         for (int g4 = 0; g4 < 4; ++g4) { const f32x4 f = *(const LAS f32x4*)(wsf + 8 * g4 + 4 * hi);
; #pragma unroll
;             for (int k = 0; k < 4; ++k) { st.o0[4 * g4 + k] *= f[k]; st.o1[4 * g4 + k] *= f[k]; if (CMP) { imp0[4 * g4 + k] *= f[k]; imp1[4 * g4 + k] *= f[k]; } } }
;         LDS_WAIT();
;     }
;     bf16x8 pa[4];
;     pa[0] = pack8(p0[0], p0[1], p0[2], p0[3], p0[4], p0[5], p0[6], p0[7]); pa[1] = pack8(p0[8], p0[9], p0[10], p0[11], p0[12], p0[13], p0[14], p0[15]);
;     pa[2] = pack8(p1[0], p1[1], p1[2], p1[3], p1[4], p1[5], p1[6], p1[7]); pa[3] = pack8(p1[8], p1[9], p1[10], p1[11], p1[12], p1[13], p1[14], p1[15]);
;     const LAS unsigned char* vb = lds + A_VT + buf * 8192 + (4 * hi + ((lane & 15) >> 2)) * 64 + ((lane >> 4) & 1) * 32 + (lane & 3) * 8;
; #pragma unroll
;     for (int s = 0; s < 4; ++s) {
;         const bf16x8 v0 = cat8(vtr(vb + s * 1024), vtr(vb + s * 1024 + 512));
;         const bf16x8 v1 = cat8(vtr(vb + 4096 + s * 1024), vtr(vb + 4096 + s * 1024 + 512));
;         st.o0 = MFMA32(pa[s], v0, st.o0); st.o1 = MFMA32(pa[s], v1, st.o1);
;     }
.LBB0_1168:
	v_cndmask_b32_e64 v229, v141, v218, s[80:81]
	v_sub_f32_e32 v84, v84, v229
	v_sub_f32_e32 v68, v68, v229
	v_exp_f32_e32 v230, v84
	v_exp_f32_e32 v68, v68
	v_sub_f32_e32 v85, v85, v229
	v_sub_f32_e32 v69, v69, v229
	v_exp_f32_e32 v85, v85
	v_exp_f32_e32 v69, v69
	v_sub_f32_e32 v86, v86, v229
	v_sub_f32_e32 v70, v70, v229
	v_exp_f32_e32 v86, v86
	v_exp_f32_e32 v70, v70
	v_sub_f32_e32 v87, v87, v229
	v_sub_f32_e32 v71, v71, v229
	v_exp_f32_e32 v87, v87
	v_exp_f32_e32 v71, v71
	v_add_f32_e32 v84, v68, v230
	v_add_f32_e32 v84, 0, v84
	v_add_f32_e32 v231, v69, v85
	v_add_f32_e32 v84, v231, v84
	v_add_f32_e32 v231, v70, v86
	v_add_f32_e32 v84, v231, v84
	v_add_f32_e32 v231, v71, v87
	v_sub_f32_e32 v88, v88, v229
	v_sub_f32_e32 v72, v72, v229
	v_add_f32_e32 v84, v231, v84
	v_exp_f32_e32 v88, v88
	v_exp_f32_e32 v231, v72
	v_sub_f32_e32 v73, v73, v229
	v_exp_f32_e32 v232, v73
	v_sub_f32_e32 v74, v74, v229
	v_add_f32_e32 v72, v231, v88
	v_add_f32_e32 v72, v72, v84
	v_sub_f32_e32 v84, v89, v229
	v_exp_f32_e32 v89, v84
	v_sub_f32_e32 v75, v75, v229
	v_exp_f32_e32 v75, v75
	v_sub_f32_e32 v76, v76, v229
	v_add_f32_e32 v73, v232, v89
	v_add_f32_e32 v72, v73, v72
	v_sub_f32_e32 v73, v90, v229
	v_exp_f32_e32 v73, v73
	v_exp_f32_e32 v90, v74
	v_sub_f32_e32 v77, v77, v229
	v_sub_f32_e32 v78, v78, v229
	v_sub_f32_e32 v79, v79, v229
	v_add_f32_e32 v74, v90, v73
	v_add_f32_e32 v72, v74, v72
	v_sub_f32_e32 v74, v91, v229
	v_exp_f32_e32 v74, v74
	v_sub_f32_e32 v80, v80, v229
	v_subrev_u32_e32 v226, 64, v226
	v_add_f32_e32 v84, v75, v74
	v_add_f32_e32 v72, v84, v72
	v_sub_f32_e32 v84, v92, v229
	v_exp_f32_e32 v91, v84
	v_exp_f32_e32 v92, v76
	v_cvt_pk_bf16_f32 v75, v90, v75
	v_add_f32_e32 v76, v92, v91
	v_add_f32_e32 v72, v76, v72
	v_sub_f32_e32 v76, v93, v229
	v_exp_f32_e32 v76, v76
	v_exp_f32_e32 v93, v77
	s_nop 0
	v_add_f32_e32 v77, v93, v76
	v_add_f32_e32 v72, v77, v72
	v_sub_f32_e32 v77, v94, v229
	v_exp_f32_e32 v77, v77
	v_exp_f32_e32 v94, v78
	v_cvt_pk_bf16_f32 v76, v91, v76
	v_add_f32_e32 v78, v94, v77
	v_add_f32_e32 v72, v78, v72
	v_sub_f32_e32 v78, v95, v229
	v_exp_f32_e32 v78, v78
	v_exp_f32_e32 v95, v79
	v_cvt_pk_bf16_f32 v77, v77, v78
	v_add_f32_e32 v79, v95, v78
	v_add_f32_e32 v72, v79, v72
	v_sub_f32_e32 v79, v96, v229
	v_exp_f32_e32 v79, v79
	v_exp_f32_e32 v96, v80
	s_nop 0
	v_add_f32_e32 v80, v96, v79
	v_add_f32_e32 v72, v80, v72
	v_sub_f32_e32 v80, v97, v229
	v_exp_f32_e32 v97, v80
	v_sub_f32_e32 v80, v81, v229
	v_exp_f32_e32 v233, v80
	v_cvt_pk_bf16_f32 v81, v86, v87
	v_cvt_pk_bf16_f32 v78, v79, v97
	v_add_f32_e32 v80, v233, v97
	v_add_f32_e32 v72, v80, v72
	v_sub_f32_e32 v80, v98, v229
	v_exp_f32_e32 v98, v80
	v_sub_f32_e32 v80, v82, v229
	v_exp_f32_e32 v234, v80
	v_cvt_pk_bf16_f32 v82, v88, v89
	v_add_f32_e32 v80, v234, v98
	v_add_f32_e32 v72, v80, v72
	v_sub_f32_e32 v80, v99, v229
	v_exp_f32_e32 v99, v80
	v_sub_f32_e32 v80, v83, v229
	v_exp_f32_e32 v229, v80
	v_cvt_pk_bf16_f32 v83, v73, v74
	v_cvt_pk_bf16_f32 v79, v98, v99
	v_cvt_pk_bf16_f32 v73, v70, v71
	v_add_f32_e32 v80, v229, v99
	v_add_f32_e32 v84, v80, v72
	v_cvt_pk_bf16_f32 v80, v230, v85
	v_add_u32_e32 v85, s28, v188
	v_add3_u32 v85, v85, v187, v186
	v_cvt_pk_bf16_f32 v72, v68, v69
	v_cvt_pk_bf16_f32 v68, v92, v93
	ds_read_b64_tr_b16 v[86:87], v85 offset:16384
	ds_read_b64_tr_b16 v[88:89], v85 offset:16896
	ds_read_b64_tr_b16 v[90:91], v85 offset:20480
	ds_read_b64_tr_b16 v[92:93], v85 offset:20992
	s_waitcnt lgkmcnt(0)
	v_mfma_f32_32x32x16_bf16 v[52:67], v[80:83], v[86:89], v[52:67]
	v_cvt_pk_bf16_f32 v74, v231, v232
	v_cvt_pk_bf16_f32 v69, v94, v95
	v_cvt_pk_bf16_f32 v70, v96, v233
	v_cvt_pk_bf16_f32 v71, v234, v229
	v_fmac_f32_e32 v84, v227, v228
	v_mfma_f32_32x32x16_bf16 v[36:51], v[80:83], v[90:93], v[36:51]
	ds_read_b64_tr_b16 v[86:87], v85 offset:17408
	ds_read_b64_tr_b16 v[88:89], v85 offset:17920
	ds_read_b64_tr_b16 v[90:91], v85 offset:21504
	ds_read_b64_tr_b16 v[92:93], v85 offset:22016
	s_waitcnt lgkmcnt(0)
	v_mfma_f32_32x32x16_bf16 v[52:67], v[76:79], v[86:89], v[52:67]
	v_mfma_f32_32x32x16_bf16 v[36:51], v[76:79], v[90:93], v[36:51]
	ds_read_b64_tr_b16 v[86:87], v85 offset:18432
	ds_read_b64_tr_b16 v[88:89], v85 offset:18944
	ds_read_b64_tr_b16 v[90:91], v85 offset:22528
	ds_read_b64_tr_b16 v[92:93], v85 offset:23040
	s_waitcnt lgkmcnt(0)
; #define MFMA32(a, b, c) __builtin_amdgcn_mfma_f32_32x32x16_bf16((a), (b), (c), 0, 0, 0)
; DI s16x4 vtr(const LAS unsigned char* p) { return __builtin_bit_cast(s16x4, __builtin_amdgcn_ds_read_tr16_b64_v4i16((LAS v4i16_t*)p)); }
; DI bf16x8 cat8(s16x4 lo, s16x4 hi) { return __builtin_shufflevector(lo, hi, 0, 1, 2, 3, 4, 5, 6, 7); }
; template <bool CMP> DI void tile_compute(LAS unsigned char* lds, int buf, const bf16x8 (&q)[4], int lo, int hv, ASt& st, f32x16& imp0, f32x16& imp1, int jt, LAS float* wsf, int lane) {
;     ...
;     for (int s = 0; s < 4; ++s) {
;         const bf16x8 v0 = cat8(vtr(vb + s * 1024), vtr(vb + s * 1024 + 512));
;         const bf16x8 v1 = cat8(vtr(vb + 4096 + s * 1024), vtr(vb + 4096 + s * 1024 + 512));
;         st.o0 = MFMA32(pa[s], v0, st.o0); st.o1 = MFMA32(pa[s], v1, st.o1);
;     }
;     if (CMP) {
; #pragma unroll
;         for (int s = 0; s < 4; ++s) {
;             bf16x8 w0, w1;
; #pragma unroll
;             for (int j = 0; j < 8; ++j) { const int jj = 64 * jt + 16 * s + 8 * (j >> 2) + 4 * hi + (j & 3);
;                 const int n0 = r, n1 = 32 + r;
;                 w0[j] = (jj >= 4 * n0 - 1 && jj <= 4 * n0 + 3) ? (short)0x3F80 : (short)0;
;                 w1[j] = (jj >= 4 * n1 - 1 && jj <= 4 * n1 + 3) ? (short)0x3F80 : (short)0; }
;             imp0 = MFMA32(pa[s], w0, imp0); imp1 = MFMA32(pa[s], w1, imp1); asm volatile("" ::: "memory");
;         }
;     }
	v_mfma_f32_32x32x16_bf16 v[52:67], v[72:75], v[86:89], v[52:67]
	v_mfma_f32_32x32x16_bf16 v[36:51], v[72:75], v[90:93], v[36:51]
	ds_read_b64_tr_b16 v[86:87], v85 offset:19456
	ds_read_b64_tr_b16 v[88:89], v85 offset:19968
	ds_read_b64_tr_b16 v[90:91], v85 offset:23552
	ds_read_b64_tr_b16 v[92:93], v85 offset:24064
	v_add_u32_e32 v85, s16, v148
	v_sub_u32_e32 v98, v85, v196
	v_mov_b32_e32 v96, 0x3f803f80
	v_mov_b32_e32 v97, 0x3f800000
	s_waitcnt lgkmcnt(0)
	v_mfma_f32_32x32x16_bf16 v[52:67], v[68:71], v[86:89], v[52:67]
	v_mfma_f32_32x32x16_bf16 v[36:51], v[68:71], v[90:93], v[36:51]
	s_add_i32 s16, s16, 64
	v_add_u32_e32 v94, 0, v98
	v_cmp_eq_u32_e32 vcc, 0, v94
	v_cmp_eq_u32_e64 s[80:81], -4, v94
	v_cmp_eq_u32_e64 s[14:15], -8, v94
	v_cndmask_b32_e32 v86, 0, v96, vcc
	v_cmp_eq_u32_e32 vcc, -12, v94
	v_cndmask_b32_e64 v87, v86, v97, s[80:81]
	v_cndmask_b32_e64 v88, 0, v96, s[14:15]
	v_cndmask_b32_e32 v89, v88, v97, vcc
	s_nop 1
	v_mfma_f32_32x32x16_bf16 v[20:35], v[80:83], v[86:89], v[20:35]
	v_add_u32_e32 v95, 0xffffff80, v98
	v_cmp_eq_u32_e32 vcc, 0, v95
	v_cmp_eq_u32_e64 s[80:81], -4, v95
	v_cmp_eq_u32_e64 s[14:15], -8, v95
	v_cndmask_b32_e32 v86, 0, v96, vcc
	v_cmp_eq_u32_e32 vcc, -12, v95
	v_cndmask_b32_e64 v87, v86, v97, s[80:81]
	v_cndmask_b32_e64 v88, 0, v96, s[14:15]
	v_cndmask_b32_e32 v89, v88, v97, vcc
	s_nop 1
	v_mfma_f32_32x32x16_bf16 v[4:19], v[80:83], v[86:89], v[4:19]
	v_add_u32_e32 v94, 16, v98
	v_cmp_eq_u32_e32 vcc, 0, v94
	v_cmp_eq_u32_e64 s[80:81], -4, v94
	v_cmp_eq_u32_e64 s[14:15], -8, v94
	v_cndmask_b32_e32 v80, 0, v96, vcc
	v_cmp_eq_u32_e32 vcc, -12, v94
	v_cndmask_b32_e64 v81, v80, v97, s[80:81]
	v_cndmask_b32_e64 v82, 0, v96, s[14:15]
	v_cndmask_b32_e32 v83, v82, v97, vcc
	s_nop 1
	v_mfma_f32_32x32x16_bf16 v[20:35], v[76:79], v[80:83], v[20:35]
	v_add_u32_e32 v95, 0xffffff90, v98
	v_cmp_eq_u32_e32 vcc, 0, v95
	v_cmp_eq_u32_e64 s[80:81], -4, v95
	v_cmp_eq_u32_e64 s[14:15], -8, v95
	v_cndmask_b32_e32 v80, 0, v96, vcc
	v_cmp_eq_u32_e32 vcc, -12, v95
	v_cndmask_b32_e64 v81, v80, v97, s[80:81]
	v_cndmask_b32_e64 v82, 0, v96, s[14:15]
	v_cndmask_b32_e32 v83, v82, v97, vcc
	s_nop 1
	v_mfma_f32_32x32x16_bf16 v[4:19], v[76:79], v[80:83], v[4:19]
	v_add_u32_e32 v94, 32, v98
	v_cmp_eq_u32_e32 vcc, 0, v94
	v_cmp_eq_u32_e64 s[80:81], -4, v94
	v_cmp_eq_u32_e64 s[14:15], -8, v94
	v_cndmask_b32_e32 v76, 0, v96, vcc
	v_cmp_eq_u32_e32 vcc, -12, v94
	v_cndmask_b32_e64 v77, v76, v97, s[80:81]
	v_cndmask_b32_e64 v78, 0, v96, s[14:15]
	v_cndmask_b32_e32 v79, v78, v97, vcc
	s_nop 1
	v_mfma_f32_32x32x16_bf16 v[20:35], v[72:75], v[76:79], v[20:35]
	v_add_u32_e32 v95, 0xffffffa0, v98
	v_cmp_eq_u32_e32 vcc, 0, v95
	v_cmp_eq_u32_e64 s[80:81], -4, v95
	v_cmp_eq_u32_e64 s[14:15], -8, v95
	v_cndmask_b32_e32 v76, 0, v96, vcc
	v_cmp_eq_u32_e32 vcc, -12, v95
	v_cndmask_b32_e64 v77, v76, v97, s[80:81]
	v_cndmask_b32_e64 v78, 0, v96, s[14:15]
	v_cndmask_b32_e32 v79, v78, v97, vcc
	s_nop 1
	v_mfma_f32_32x32x16_bf16 v[4:19], v[72:75], v[76:79], v[4:19]
	s_add_u32 s88, s88, 0x2000
	s_addc_u32 s89, s89, 0
	v_add_u32_e32 v94, 48, v98
	v_cmp_eq_u32_e32 vcc, 0, v94
	v_cmp_eq_u32_e64 s[80:81], -4, v94
	v_cmp_eq_u32_e64 s[14:15], -8, v94
	v_cndmask_b32_e32 v72, 0, v96, vcc
	v_cmp_eq_u32_e32 vcc, -12, v94
	v_cndmask_b32_e64 v73, v72, v97, s[80:81]
	v_cndmask_b32_e64 v74, 0, v96, s[14:15]
	v_cndmask_b32_e32 v75, v74, v97, vcc
	s_nop 1
	v_mfma_f32_32x32x16_bf16 v[20:35], v[68:71], v[72:75], v[20:35]
	s_add_i32 s6, s6, 1
	s_cmp_eq_u32 s90, s16
	v_add_u32_e32 v95, 0xffffffb0, v98
	v_cmp_eq_u32_e32 vcc, 0, v95
	v_cmp_eq_u32_e64 s[80:81], -4, v95
	v_cmp_eq_u32_e64 s[14:15], -8, v95
	v_cndmask_b32_e32 v72, 0, v96, vcc
	v_cmp_eq_u32_e32 vcc, -12, v95
	v_cndmask_b32_e64 v73, v72, v97, s[80:81]
	v_cndmask_b32_e64 v74, 0, v96, s[14:15]
	v_cndmask_b32_e32 v75, v74, v97, vcc
	s_nop 1
	v_mfma_f32_32x32x16_bf16 v[4:19], v[68:71], v[72:75], v[4:19]
	s_cbranch_scc1 .LBB0_1170
	v_mov_b32_e32 v227, v84
	v_mov_b32_e32 v228, v141
	s_branch .LBB0_1160
